# dn_prep step 3 tile loop rewritten branch-free: all 11 LDS reads batched up front, 4 decay exps interleaved, same product order
# speedup vs baseline: 1.0307x; 1.0092x over previous
; #define MFMA16(a, b, c) __builtin_amdgcn_mfma_f32_16x16x32_bf16((a), (b), (c), 0, 0, 0)
; DI void dn_prep_item(const Params& p, int l, int item, int next_item, u32x4 (&pre)[12], unsigned char* lds, int tid) {
;     ...
;         const int wv = tid >> 6, c = lane & 15, g = lane >> 4;
;         for (int t = wv; t < 20; t += 8) { const int isq = t >= 10, tt = isq ? t - 10 : t, it = (tt >= 6) ? 3 : ((tt >= 3) ? 2 : ((tt >= 1) ? 1 : 0)), jt = tt - it * (it + 1) / 2;
;             const bf16_t* XHp = (isq ? QH : KH) + (16 * it + c) * 72 + 8 * g; const bf16_t* XLp = (isq ? QL : KL) + (16 * it + c) * 72 + 8 * g;
;             const bf16_t* KHp = KH + (16 * jt + c) * 72 + 8 * g; const bf16_t* KLp = KL + (16 * jt + c) * 72 + 8 * g;
;             f32x4 acc = (f32x4){zz, zz, zz, zz};
; #pragma unroll
;             for (int s = 0; s < 2; ++s) { const bf16x8 xh = *(const bf16x8*)(XHp + 32 * s), xl = *(const bf16x8*)(XLp + 32 * s), kh = *(const bf16x8*)(KHp + 32 * s), kl = *(const bf16x8*)(KLp + 32 * s);
;                 acc = MFMA16(xl, kh, acc); acc = MFMA16(xh, kl, acc); acc = MFMA16(xh, kh, acc); }
;             const int jj = 16 * jt + c; const float gj = Gs[jj];
; #pragma unroll
;             for (int rr = 0; rr < 4; ++rr) { const int ii = 16 * it + 4 * g + rr; const float dec = (jj <= ii) ? expf(Gs[ii] - gj) : 0.f;
;                 if (isq) AIs[ii * 64 + jj] = (jj <= ii) ? acc[rr] * dec : 0.f; else Ls[ii * 64 + jj] = (jj < ii) ? BETAs[ii] * acc[rr] * dec : 0.f; } }
.LBB0_318:
	v_cmp_lt_i32_e64 s[6:7], 9, v13
	v_add_u32_e32 v4, -10, v13
	v_cmp_gt_i32_e32 vcc, 10, v13
	v_cndmask_b32_e64 v4, v13, v4, s[6:7]
	v_cmp_lt_i32_e64 s[8:9], 0, v4
	s_nop 1
	v_cndmask_b32_e64 v5, 0, 1, s[8:9]
	v_cmp_gt_i32_e64 s[8:9], 3, v4
	s_nop 1
	v_cndmask_b32_e64 v5, 2, v5, s[8:9]
	v_cmp_gt_i32_e64 s[8:9], 6, v4
	s_nop 1
	v_cndmask_b32_e64 v5, 3, v5, s[8:9]
	v_add_u32_e32 v6, 1, v5
	v_mul_u32_u24_e32 v6, v6, v5
	v_lshlrev_b32_e32 v28, 4, v5
	v_lshrrev_b32_e32 v6, 1, v6
	v_or_b32_e32 v5, v28, v61
	v_sub_u32_e32 v4, v4, v6
	v_mul_u32_u24_e32 v5, 0x48, v5
	v_cndmask_b32_e64 v6, v71, v73, s[6:7]
	v_lshlrev_b32_e32 v5, 1, v5
	v_lshl_or_b32 v14, v4, 4, v61
	v_add3_u32 v15, v6, v5, v12
	v_cndmask_b32_e64 v6, v72, v74, s[6:7]
	v_mul_lo_u32 v4, v14, s56
	v_add3_u32 v29, v6, v5, v12
	v_add_u32_e32 v31, v9, v4
	v_add_u32_e32 v32, v10, v4
	ds_read_b128 v[212:215], v15
	ds_read_b128 v[216:219], v29
	ds_read_b128 v[220:223], v31
	ds_read_b128 v[224:227], v32
	v_or_b32_e32 v17, v28, v11
	v_lshl_add_u32 v4, v14, 2, v68
	v_lshl_add_u32 v5, v17, 2, v68
	v_lshl_add_u32 v6, v17, 2, v69
	ds_read_b32 v28, v4
	ds_read_b128 v[20:23], v5
	ds_read_b128 v[24:27], v6
	ds_read_b128 v[228:231], v15 offset:64
	ds_read_b128 v[232:235], v29 offset:64
	ds_read_b128 v[236:239], v31 offset:64
	ds_read_b128 v[240:243], v32 offset:64
	v_cndmask_b32_e64 v31, 0, 1, s[6:7]
	v_sub_u32_e32 v29, v17, v14
	v_cndmask_b32_e64 v32, v51, v53, s[6:7]
	v_lshlrev_b32_e32 v15, 8, v17
	v_add_u32_e32 v29, v29, v31
	v_lshlrev_b32_e32 v31, 2, v14
	v_add3_u32 v32, v32, v15, v31
	s_waitcnt lgkmcnt(8)
	v_mfma_f32_16x16x32_bf16 v[16:19], v[216:219], v[220:223], v[0:3]
	s_waitcnt lgkmcnt(7)
	v_mfma_f32_16x16x32_bf16 v[16:19], v[212:215], v[224:227], v[16:19]
	v_mfma_f32_16x16x32_bf16 v[4:7], v[212:215], v[220:223], v[16:19]
	s_waitcnt lgkmcnt(4)
	v_cndmask_b32_e64 v24, v24, 1.0, s[6:7]
	v_cndmask_b32_e64 v25, v25, 1.0, s[6:7]
	v_cndmask_b32_e64 v26, v26, 1.0, s[6:7]
	v_cndmask_b32_e64 v27, v27, 1.0, s[6:7]
	v_sub_f32_e32 v20, v20, v28
	v_sub_f32_e32 v21, v21, v28
	v_sub_f32_e32 v22, v22, v28
	v_sub_f32_e32 v23, v23, v28
	v_mul_f32_e32 v212, 0x3fb8aa3b, v20
	v_mul_f32_e32 v213, 0x3fb8aa3b, v21
	v_mul_f32_e32 v214, 0x3fb8aa3b, v22
	v_mul_f32_e32 v215, 0x3fb8aa3b, v23
	v_rndne_f32_e32 v220, v212
	v_rndne_f32_e32 v221, v213
	v_rndne_f32_e32 v222, v214
	v_rndne_f32_e32 v223, v215
	v_fma_f32 v216, v20, s88, -v212
	v_fma_f32 v217, v21, s88, -v213
	v_fma_f32 v218, v22, s88, -v214
	v_fma_f32 v219, v23, s88, -v215
	v_fmac_f32_e32 v216, 0x32a5705f, v20
	v_fmac_f32_e32 v217, 0x32a5705f, v21
	v_fmac_f32_e32 v218, 0x32a5705f, v22
	v_fmac_f32_e32 v219, 0x32a5705f, v23
	v_sub_f32_e32 v212, v212, v220
	v_sub_f32_e32 v213, v213, v221
	v_sub_f32_e32 v214, v214, v222
	v_sub_f32_e32 v215, v215, v223
	v_add_f32_e32 v212, v212, v216
	v_add_f32_e32 v213, v213, v217
	v_add_f32_e32 v214, v214, v218
	v_add_f32_e32 v215, v215, v219
	s_waitcnt lgkmcnt(1)
	v_mfma_f32_16x16x32_bf16 v[4:7], v[232:235], v[236:239], v[4:7]
	v_cvt_i32_f32_e32 v220, v220
	v_cvt_i32_f32_e32 v221, v221
	v_cvt_i32_f32_e32 v222, v222
	v_cvt_i32_f32_e32 v223, v223
	s_waitcnt lgkmcnt(0)
	v_mfma_f32_16x16x32_bf16 v[4:7], v[228:231], v[240:243], v[4:7]
	v_exp_f32_e32 v212, v212
	v_exp_f32_e32 v213, v213
	v_exp_f32_e32 v214, v214
	v_exp_f32_e32 v215, v215
	v_mfma_f32_16x16x32_bf16 v[4:7], v[228:231], v[236:239], v[4:7]
	v_ldexp_f32 v212, v212, v220
	v_ldexp_f32 v213, v213, v221
	v_ldexp_f32 v214, v214, v222
	v_ldexp_f32 v215, v215, v223
	v_cmp_ngt_f32_e64 s[8:9], s79, v20
	v_cmp_ngt_f32_e64 s[10:11], s79, v21
	v_cmp_ngt_f32_e64 s[30:31], s79, v22
	v_cmp_ngt_f32_e64 s[34:35], s79, v23
	v_cndmask_b32_e64 v212, 0, v212, s[8:9]
	v_cndmask_b32_e64 v213, 0, v213, s[10:11]
	v_cndmask_b32_e64 v214, 0, v214, s[30:31]
	v_cndmask_b32_e64 v215, 0, v215, s[34:35]
	v_cmp_nlt_f32_e64 s[8:9], s54, v20
	v_cmp_nlt_f32_e64 s[10:11], s54, v21
	v_cmp_nlt_f32_e64 s[30:31], s54, v22
	v_cmp_nlt_f32_e64 s[34:35], s54, v23
	v_cndmask_b32_e64 v212, v210, v212, s[8:9]
	v_cndmask_b32_e64 v213, v210, v213, s[10:11]
	v_cndmask_b32_e64 v214, v210, v214, s[30:31]
	v_cndmask_b32_e64 v215, v210, v215, s[34:35]
	v_cmp_lt_i32_e64 s[8:9], 0, v29
	v_cmp_lt_i32_e64 s[10:11], -1, v29
	v_cmp_lt_i32_e64 s[30:31], -2, v29
	v_cmp_lt_i32_e64 s[34:35], -3, v29
	v_mul_f32_e32 v36, v4, v24
	v_mul_f32_e32 v37, v5, v25
	v_mul_f32_e32 v38, v6, v26
	v_mul_f32_e32 v39, v7, v27
	v_mul_f32_e32 v36, v212, v36
	v_mul_f32_e32 v37, v213, v37
	v_mul_f32_e32 v38, v214, v38
	v_mul_f32_e32 v39, v215, v39
	v_cndmask_b32_e64 v36, 0, v36, s[8:9]
	v_cndmask_b32_e64 v37, 0, v37, s[10:11]
	v_cndmask_b32_e64 v38, 0, v38, s[30:31]
	v_cndmask_b32_e64 v39, 0, v39, s[34:35]
	ds_write_b32 v32, v36
	ds_write_b32 v32, v37 offset:256
	ds_write_b32 v32, v38 offset:512
	ds_write_b32 v32, v39 offset:768
	v_cmp_lt_i32_e32 vcc, 11, v13
	v_add_u32_e32 v13, 8, v13
	s_or_b64 s[14:15], vcc, s[14:15]
	s_andn2_b64 exec, exec, s[14:15]
	s_cbranch_execnz .LBB0_318
